# 64-row attention as in v53 plus an explicit lgkmcnt wait before the first PV MFMAs (emitter keeps pending LDS reads across conditionally skipped regions)
# baseline (speedup 1.0000x reference)
; __device__ __forceinline__ void partialSM(f32x16& p0, f32x16& p1, float& m_reg, float& mn, float& alpha) {
;     constexpr float Cc = SCALE * 1.4426950408889634f;
;     float pmax = p0[0];
; #pragma unroll
;     for (int r = 1; r < 16; ++r) pmax = fmaxf(pmax, p0[r]);
; #pragma unroll
;     for (int r = 0; r < 16; ++r) pmax = fmaxf(pmax, p1[r]);
;     { auto rr = __builtin_amdgcn_permlane32_swap(__float_as_uint(pmax), __float_as_uint(pmax), false, false);
;       pmax = fmaxf(__uint_as_float(rr[0]), __uint_as_float(rr[1])); }
;     if (__builtin_expect(__all(pmax - m_reg <= THR / SCALE), 1)) { mn = m_reg; alpha = 1.f; }
;     else { mn = fmaxf(m_reg, pmax); alpha = __builtin_amdgcn_exp2f((m_reg - mn) * Cc); m_reg = mn; }
;     const float mnC = -mn * Cc;
;     { typedef float f32x2 __attribute__((ext_vector_type(2))); const f32x2 c2 = {Cc, Cc}, m2 = {mnC, mnC};
; #pragma unroll
;       for (int r = 0; r < 16; r += 2) { f32x2 t = {p0[r], p0[r + 1]}; t = __builtin_elementwise_fma(t, c2, m2); p0[r] = t.x; p0[r + 1] = t.y; }
; #pragma unroll
;       for (int r = 0; r < 16; r += 2) { f32x2 t = {p1[r], p1[r + 1]}; t = __builtin_elementwise_fma(t, c2, m2); p1[r] = t.x; p1[r + 1] = t.y; } }
; #pragma unroll
;     for (int r = 0; r < 16; ++r) p0[r] = __builtin_amdgcn_exp2f(p0[r]);
; }
; __device__ __forceinline__ void finishSM(f32x16& p0, f32x16& p1, float alpha, float& l_reg, bf16x8& pa0, bf16x8& pa1, bf16x8& pa2, bf16x8& pa3) {
; #pragma unroll
;     for (int r = 0; r < 16; ++r) p1[r] = __builtin_amdgcn_exp2f(p1[r]);
;     float ps;
;     { typedef float f32x2 __attribute__((ext_vector_type(2))); f32x2 s0 = {p0[0], p0[1]}, s1 = {p1[0], p1[1]};
; #pragma unroll
;       for (int r = 2; r < 16; r += 2) { s0 += (f32x2){p0[r], p0[r + 1]}; s1 += (f32x2){p1[r], p1[r + 1]}; }
;       s0 += s1; ps = s0.x + s0.y; }
;     { auto rr = __builtin_amdgcn_permlane32_swap(__float_as_uint(ps), __float_as_uint(ps), false, false);
;       ps = __uint_as_float(rr[0]) + __uint_as_float(rr[1]); }
;     l_reg = l_reg * alpha + ps;
;     ...
;     PK4(p0, 0, pa0); PK4(p0, 8, pa1); PK4(p1, 0, pa2); PK4(p1, 8, pa3);
;     ...
; }
.LA_nosw:
	v_add_u32_e32 v202, s18, v235
	v_max_f32_e32 v212, v66, v67
	v_max_f32_e32 v213, v82, v83
	v_max3_f32 v212, v212, v68, v69
	v_max3_f32 v213, v213, v84, v85
	v_max3_f32 v212, v212, v70, v71
	v_max3_f32 v213, v213, v86, v87
	v_max3_f32 v212, v212, v72, v73
	v_max3_f32 v213, v213, v88, v89
	v_max3_f32 v212, v212, v74, v75
	v_max3_f32 v213, v213, v90, v91
	v_max3_f32 v212, v212, v76, v77
	v_max3_f32 v213, v213, v92, v93
	v_max3_f32 v212, v212, v78, v79
	v_max3_f32 v213, v213, v94, v95
	v_max3_f32 v212, v212, v80, v81
	v_max3_f32 v213, v213, v96, v97
	v_max_f32_e32 v212, v212, v213
	v_mov_b32_e32 v213, v212
	s_nop 1
	v_permlane32_swap_b32_e32 v212, v213
	v_max_f32_e32 v212, v212, v213
	v_sub_f32_e32 v214, v212, v141
	v_cmp_ge_f32_e32 vcc, s67, v214
	v_max_f32_e32 v212, v141, v212
	v_sub_f32_e32 v214, v141, v212
	v_mul_f32_e32 v214, 0x3e16c740, v214
	v_exp_f32_e32 v215, v214
	s_cmp_eq_u64 vcc, exec
	s_cselect_b64 s[58:59], -1, 0
	v_cndmask_b32_e64 v141, v212, v141, s[58:59]
	v_cndmask_b32_e64 v215, v215, 1.0, s[58:59]
	v_mul_f32_e32 v216, 0xbe16c740, v141
	v_fma_f32 v66, v66, s52, v216
	v_fma_f32 v67, v67, s52, v216
	v_fma_f32 v68, v68, s52, v216
	v_fma_f32 v69, v69, s52, v216
	v_fma_f32 v70, v70, s52, v216
	v_fma_f32 v71, v71, s52, v216
	v_fma_f32 v72, v72, s52, v216
	v_fma_f32 v73, v73, s52, v216
	v_fma_f32 v74, v74, s52, v216
	v_fma_f32 v75, v75, s52, v216
	v_fma_f32 v76, v76, s52, v216
	v_fma_f32 v77, v77, s52, v216
	v_fma_f32 v78, v78, s52, v216
	v_fma_f32 v79, v79, s52, v216
	v_fma_f32 v80, v80, s52, v216
	v_fma_f32 v81, v81, s52, v216
	v_fma_f32 v82, v82, s52, v216
	v_fma_f32 v83, v83, s52, v216
	v_fma_f32 v84, v84, s52, v216
	v_fma_f32 v85, v85, s52, v216
	v_fma_f32 v86, v86, s52, v216
	v_fma_f32 v87, v87, s52, v216
	v_fma_f32 v88, v88, s52, v216
	v_fma_f32 v89, v89, s52, v216
	v_fma_f32 v90, v90, s52, v216
	v_fma_f32 v91, v91, s52, v216
	v_fma_f32 v92, v92, s52, v216
	v_fma_f32 v93, v93, s52, v216
	v_fma_f32 v94, v94, s52, v216
	v_fma_f32 v95, v95, s52, v216
	v_fma_f32 v96, v96, s52, v216
	v_fma_f32 v97, v97, s52, v216
	v_exp_f32_e32 v66, v66
	v_exp_f32_e32 v67, v67
	v_exp_f32_e32 v68, v68
	v_exp_f32_e32 v69, v69
	v_exp_f32_e32 v70, v70
	v_exp_f32_e32 v71, v71
	v_exp_f32_e32 v72, v72
	v_exp_f32_e32 v73, v73
	v_exp_f32_e32 v74, v74
	v_exp_f32_e32 v75, v75
	v_exp_f32_e32 v76, v76
	v_exp_f32_e32 v77, v77
	v_exp_f32_e32 v78, v78
	v_exp_f32_e32 v79, v79
	v_exp_f32_e32 v80, v80
	v_exp_f32_e32 v81, v81
	v_exp_f32_e32 v82, v82
	v_exp_f32_e32 v83, v83
	v_exp_f32_e32 v84, v84
	v_exp_f32_e32 v85, v85
	v_exp_f32_e32 v86, v86
	v_exp_f32_e32 v87, v87
	v_exp_f32_e32 v88, v88
	v_exp_f32_e32 v89, v89
	v_exp_f32_e32 v90, v90
	v_exp_f32_e32 v91, v91
	v_exp_f32_e32 v92, v92
	v_exp_f32_e32 v93, v93
	v_exp_f32_e32 v94, v94
	v_exp_f32_e32 v95, v95
	v_exp_f32_e32 v96, v96
	v_exp_f32_e32 v97, v97
	v_add_f32_e32 v212, v66, v68
	v_add_f32_e32 v213, v67, v69
	v_add_f32_e32 v212, v70, v212
	v_add_f32_e32 v213, v71, v213
	v_add_f32_e32 v212, v72, v212
	v_add_f32_e32 v213, v73, v213
	v_add_f32_e32 v212, v74, v212
	v_add_f32_e32 v213, v75, v213
	v_add_f32_e32 v212, v76, v212
	v_add_f32_e32 v213, v77, v213
	v_add_f32_e32 v212, v78, v212
	v_add_f32_e32 v213, v79, v213
	v_add_f32_e32 v212, v80, v212
	v_add_f32_e32 v213, v81, v213
	v_add_f32_e32 v212, v82, v212
	v_add_f32_e32 v213, v83, v213
	v_add_f32_e32 v212, v84, v212
	v_add_f32_e32 v213, v85, v213
	v_add_f32_e32 v212, v86, v212
	v_add_f32_e32 v213, v87, v213
	v_add_f32_e32 v212, v88, v212
	v_add_f32_e32 v213, v89, v213
	v_add_f32_e32 v212, v90, v212
	v_add_f32_e32 v213, v91, v213
	v_add_f32_e32 v212, v92, v212
	v_add_f32_e32 v213, v93, v213
	v_add_f32_e32 v212, v94, v212
	v_add_f32_e32 v213, v95, v213
	v_add_f32_e32 v212, v96, v212
	v_add_f32_e32 v213, v97, v213
	v_add_f32_e32 v212, v212, v213
	v_fma_f32 v254, v254, v215, v212
	v_cvt_pk_bf16_f32 v66, v66, v67
	v_cvt_pk_bf16_f32 v67, v68, v69
	v_cvt_pk_bf16_f32 v68, v70, v71
	v_cvt_pk_bf16_f32 v69, v72, v73
	v_cvt_pk_bf16_f32 v70, v74, v75
	v_cvt_pk_bf16_f32 v71, v76, v77
	v_cvt_pk_bf16_f32 v72, v78, v79
	v_cvt_pk_bf16_f32 v73, v80, v81
	v_cvt_pk_bf16_f32 v82, v82, v83
	v_cvt_pk_bf16_f32 v83, v84, v85
	v_cvt_pk_bf16_f32 v84, v86, v87
	v_cvt_pk_bf16_f32 v85, v88, v89
	v_cvt_pk_bf16_f32 v86, v90, v91
	v_cvt_pk_bf16_f32 v87, v92, v93
	v_cvt_pk_bf16_f32 v88, v94, v95
	v_cvt_pk_bf16_f32 v89, v96, v97
	v_permlane32_swap_b32_e32 v66, v68
	v_permlane32_swap_b32_e32 v67, v69
	v_permlane32_swap_b32_e32 v70, v72
	v_permlane32_swap_b32_e32 v71, v73
	v_permlane32_swap_b32_e32 v82, v84
	v_permlane32_swap_b32_e32 v83, v85
	v_permlane32_swap_b32_e32 v86, v88
	v_permlane32_swap_b32_e32 v87, v89
	v_cmp_gt_f32_e32 vcc, 1.0, v215
	s_cbranch_vccz .LA_rs0
	s_and_saveexec_b64 s[60:61], s[4:5]
	ds_write_b32 v234, v215 offset:128
	s_or_b64 exec, exec, s[60:61]
	s_waitcnt lgkmcnt(0)
	v_add_u32_e32 v245, v232, v233
	ds_read_b128 v[220:223], v245 offset:224
	ds_read_b128 v[224:227], v245 offset:192
	ds_read_b128 v[216:219], v245 offset:160
	ds_read_b128 v[212:215], v245 offset:128
	s_waitcnt lgkmcnt(0)
	s_waitcnt lgkmcnt(3)
	v_mul_f32_e32 v12, v12, v220
	v_mul_f32_e32 v13, v13, v221
	v_mul_f32_e32 v14, v14, v222
	v_mul_f32_e32 v15, v15, v223
	s_waitcnt lgkmcnt(2)
	v_mul_f32_e32 v8, v8, v224
	v_mul_f32_e32 v9, v9, v225
	v_mul_f32_e32 v10, v10, v226
	v_mul_f32_e32 v11, v11, v227
	s_waitcnt lgkmcnt(1)
	v_mul_f32_e32 v4, v4, v216
	v_mul_f32_e32 v5, v5, v217
	v_mul_f32_e32 v6, v6, v218
	v_mul_f32_e32 v7, v7, v219
	s_waitcnt lgkmcnt(0)
	v_mul_f32_e32 v0, v0, v212
	v_mul_f32_e32 v1, v1, v213
	v_mul_f32_e32 v2, v2, v214
	v_mul_f32_e32 v3, v3, v215
	v_mul_f32_e32 v28, v28, v220
	v_mul_f32_e32 v29, v29, v221
	v_mul_f32_e32 v30, v30, v222
	v_mul_f32_e32 v31, v31, v223
	v_mul_f32_e32 v24, v24, v224
	v_mul_f32_e32 v25, v25, v225
	v_mul_f32_e32 v26, v26, v226
	v_mul_f32_e32 v27, v27, v227
	v_mul_f32_e32 v20, v20, v216
	v_mul_f32_e32 v21, v21, v217
	v_mul_f32_e32 v22, v22, v218
	v_mul_f32_e32 v23, v23, v219
	v_mul_f32_e32 v16, v16, v212
	v_mul_f32_e32 v17, v17, v213
	v_mul_f32_e32 v18, v18, v214
	v_mul_f32_e32 v19, v19, v215

; __device__ __forceinline__ void partialSM(f32x16& p0, f32x16& p1, float& m_reg, float& mn, float& alpha) {
;     constexpr float Cc = SCALE * 1.4426950408889634f;
;     float pmax = p0[0];
; #pragma unroll
;     for (int r = 1; r < 16; ++r) pmax = fmaxf(pmax, p0[r]);
; #pragma unroll
;     for (int r = 0; r < 16; ++r) pmax = fmaxf(pmax, p1[r]);
;     { auto rr = __builtin_amdgcn_permlane32_swap(__float_as_uint(pmax), __float_as_uint(pmax), false, false);
;       pmax = fmaxf(__uint_as_float(rr[0]), __uint_as_float(rr[1])); }
;     if (__builtin_expect(__all(pmax - m_reg <= THR / SCALE), 1)) { mn = m_reg; alpha = 1.f; }
;     else { mn = fmaxf(m_reg, pmax); alpha = __builtin_amdgcn_exp2f((m_reg - mn) * Cc); m_reg = mn; }
;     const float mnC = -mn * Cc;
;     { typedef float f32x2 __attribute__((ext_vector_type(2))); const f32x2 c2 = {Cc, Cc}, m2 = {mnC, mnC};
; #pragma unroll
;       for (int r = 0; r < 16; r += 2) { f32x2 t = {p0[r], p0[r + 1]}; t = __builtin_elementwise_fma(t, c2, m2); p0[r] = t.x; p0[r + 1] = t.y; }
; #pragma unroll
;       for (int r = 0; r < 16; r += 2) { f32x2 t = {p1[r], p1[r + 1]}; t = __builtin_elementwise_fma(t, c2, m2); p1[r] = t.x; p1[r + 1] = t.y; } }
; #pragma unroll
;     for (int r = 0; r < 16; ++r) p0[r] = __builtin_amdgcn_exp2f(p0[r]);
; }
; __device__ __forceinline__ void finishSM(f32x16& p0, f32x16& p1, float alpha, float& l_reg, bf16x8& pa0, bf16x8& pa1, bf16x8& pa2, bf16x8& pa3) {
; #pragma unroll
;     for (int r = 0; r < 16; ++r) p1[r] = __builtin_amdgcn_exp2f(p1[r]);
;     float ps;
;     { typedef float f32x2 __attribute__((ext_vector_type(2))); f32x2 s0 = {p0[0], p0[1]}, s1 = {p1[0], p1[1]};
; #pragma unroll
;       for (int r = 2; r < 16; r += 2) { s0 += (f32x2){p0[r], p0[r + 1]}; s1 += (f32x2){p1[r], p1[r + 1]}; }
;       s0 += s1; ps = s0.x + s0.y; }
;     { auto rr = __builtin_amdgcn_permlane32_swap(__float_as_uint(ps), __float_as_uint(ps), false, false);
;       ps = __uint_as_float(rr[0]) + __uint_as_float(rr[1]); }
;     l_reg = l_reg * alpha + ps;
;     ...
;     PK4(p0, 0, pa0); PK4(p0, 8, pa1); PK4(p1, 0, pa2); PK4(p1, 8, pa3);
;     ...
; }
.LA_g1b:
	ds_read_b64_tr_b16 v[74:75], v202 offset:0
	ds_read_b64_tr_b16 v[76:77], v202 offset:2048
	ds_read_b64_tr_b16 v[78:79], v202 offset:4096
	ds_read_b64_tr_b16 v[80:81], v202 offset:6144
	ds_read_b64_tr_b16 v[90:91], v202 offset:8192
	ds_read_b64_tr_b16 v[92:93], v202 offset:10240
	ds_read_b64_tr_b16 v[94:95], v202 offset:12288
	ds_read_b64_tr_b16 v[96:97], v202 offset:14336
	v_max_f32_e32 v212, v98, v99
	v_max_f32_e32 v213, v114, v115
	v_max3_f32 v212, v212, v100, v101
	v_max3_f32 v213, v213, v116, v117
	v_max3_f32 v212, v212, v102, v103
	v_max3_f32 v213, v213, v118, v119
	v_max3_f32 v212, v212, v104, v105
	v_max3_f32 v213, v213, v120, v121
	v_max3_f32 v212, v212, v106, v107
	v_max3_f32 v213, v213, v122, v123
	v_max3_f32 v212, v212, v108, v109
	v_max3_f32 v213, v213, v124, v125
	v_max3_f32 v212, v212, v110, v111
	v_max3_f32 v213, v213, v126, v127
	v_max3_f32 v212, v212, v112, v113
	v_max3_f32 v213, v213, v128, v129
	v_max_f32_e32 v212, v212, v213
	v_mov_b32_e32 v213, v212
	s_nop 1
	v_permlane32_swap_b32_e32 v212, v213
	v_max_f32_e32 v212, v212, v213
	v_sub_f32_e32 v214, v212, v139
	v_cmp_ge_f32_e32 vcc, s67, v214
	v_max_f32_e32 v212, v139, v212
	v_sub_f32_e32 v214, v139, v212
	v_mul_f32_e32 v214, 0x3e16c740, v214
	v_exp_f32_e32 v215, v214
	s_cmp_eq_u64 vcc, exec
	s_cselect_b64 s[58:59], -1, 0
	v_cndmask_b32_e64 v139, v212, v139, s[58:59]
	v_cndmask_b32_e64 v215, v215, 1.0, s[58:59]
	v_mul_f32_e32 v216, 0xbe16c740, v139
	v_fma_f32 v98, v98, s52, v216
	v_fma_f32 v99, v99, s52, v216
	v_fma_f32 v100, v100, s52, v216
	v_fma_f32 v101, v101, s52, v216
	v_fma_f32 v102, v102, s52, v216
	v_fma_f32 v103, v103, s52, v216
	v_fma_f32 v104, v104, s52, v216
	v_fma_f32 v105, v105, s52, v216
	v_fma_f32 v106, v106, s52, v216
	v_fma_f32 v107, v107, s52, v216
	v_fma_f32 v108, v108, s52, v216
	v_fma_f32 v109, v109, s52, v216
	v_fma_f32 v110, v110, s52, v216
	v_fma_f32 v111, v111, s52, v216
	v_fma_f32 v112, v112, s52, v216
	v_fma_f32 v113, v113, s52, v216
	v_fma_f32 v114, v114, s52, v216
	v_fma_f32 v115, v115, s52, v216
	v_fma_f32 v116, v116, s52, v216
	v_fma_f32 v117, v117, s52, v216
	v_fma_f32 v118, v118, s52, v216
	v_fma_f32 v119, v119, s52, v216
	v_fma_f32 v120, v120, s52, v216
	v_fma_f32 v121, v121, s52, v216
	v_fma_f32 v122, v122, s52, v216
	v_fma_f32 v123, v123, s52, v216
	v_fma_f32 v124, v124, s52, v216
	v_fma_f32 v125, v125, s52, v216
	v_fma_f32 v126, v126, s52, v216
	v_fma_f32 v127, v127, s52, v216
	v_fma_f32 v128, v128, s52, v216
	v_fma_f32 v129, v129, s52, v216
	v_exp_f32_e32 v98, v98
	v_exp_f32_e32 v99, v99
	v_exp_f32_e32 v100, v100
	v_exp_f32_e32 v101, v101
	v_exp_f32_e32 v102, v102
	v_exp_f32_e32 v103, v103
	v_exp_f32_e32 v104, v104
	v_exp_f32_e32 v105, v105
	v_exp_f32_e32 v106, v106
	v_exp_f32_e32 v107, v107
	v_exp_f32_e32 v108, v108
	v_exp_f32_e32 v109, v109
	v_exp_f32_e32 v110, v110
	v_exp_f32_e32 v111, v111
	v_exp_f32_e32 v112, v112
	v_exp_f32_e32 v113, v113
	v_exp_f32_e32 v114, v114
	v_exp_f32_e32 v115, v115
	v_exp_f32_e32 v116, v116
	v_exp_f32_e32 v117, v117
	v_exp_f32_e32 v118, v118
	v_exp_f32_e32 v119, v119
	v_exp_f32_e32 v120, v120
	v_exp_f32_e32 v121, v121
	v_exp_f32_e32 v122, v122
	v_exp_f32_e32 v123, v123
	v_exp_f32_e32 v124, v124
	v_exp_f32_e32 v125, v125
	v_exp_f32_e32 v126, v126
	v_exp_f32_e32 v127, v127
	v_exp_f32_e32 v128, v128
	v_exp_f32_e32 v129, v129
	v_add_f32_e32 v212, v98, v100
	v_add_f32_e32 v213, v99, v101
	v_add_f32_e32 v212, v102, v212
	v_add_f32_e32 v213, v103, v213
	v_add_f32_e32 v212, v104, v212
	v_add_f32_e32 v213, v105, v213
	v_add_f32_e32 v212, v106, v212
	v_add_f32_e32 v213, v107, v213
	v_add_f32_e32 v212, v108, v212
	v_add_f32_e32 v213, v109, v213
	v_add_f32_e32 v212, v110, v212
	v_add_f32_e32 v213, v111, v213
	v_add_f32_e32 v212, v112, v212
	v_add_f32_e32 v213, v113, v213
	v_add_f32_e32 v212, v114, v212
	v_add_f32_e32 v213, v115, v213
	v_add_f32_e32 v212, v116, v212
	v_add_f32_e32 v213, v117, v213
	v_add_f32_e32 v212, v118, v212
	v_add_f32_e32 v213, v119, v213
	v_add_f32_e32 v212, v120, v212
	v_add_f32_e32 v213, v121, v213
	v_add_f32_e32 v212, v122, v212
	v_add_f32_e32 v213, v123, v213
	v_add_f32_e32 v212, v124, v212
	v_add_f32_e32 v213, v125, v213
	v_add_f32_e32 v212, v126, v212
	v_add_f32_e32 v213, v127, v213
	v_add_f32_e32 v212, v128, v212
	v_add_f32_e32 v213, v129, v213
	v_add_f32_e32 v212, v212, v213
	v_fma_f32 v255, v255, v215, v212
	v_cvt_pk_bf16_f32 v98, v98, v99
	v_cvt_pk_bf16_f32 v99, v100, v101
	v_cvt_pk_bf16_f32 v100, v102, v103
	v_cvt_pk_bf16_f32 v101, v104, v105
	v_cvt_pk_bf16_f32 v102, v106, v107
	v_cvt_pk_bf16_f32 v103, v108, v109
	v_cvt_pk_bf16_f32 v104, v110, v111
	v_cvt_pk_bf16_f32 v105, v112, v113
	v_cvt_pk_bf16_f32 v114, v114, v115
	v_cvt_pk_bf16_f32 v115, v116, v117
	v_cvt_pk_bf16_f32 v116, v118, v119
	v_cvt_pk_bf16_f32 v117, v120, v121
	v_cvt_pk_bf16_f32 v118, v122, v123
	v_cvt_pk_bf16_f32 v119, v124, v125
	v_cvt_pk_bf16_f32 v120, v126, v127
	v_cvt_pk_bf16_f32 v121, v128, v129
	v_permlane32_swap_b32_e32 v98, v100
	v_permlane32_swap_b32_e32 v99, v101
	v_permlane32_swap_b32_e32 v102, v104
	v_permlane32_swap_b32_e32 v103, v105
	v_permlane32_swap_b32_e32 v114, v116
	v_permlane32_swap_b32_e32 v115, v117
	v_permlane32_swap_b32_e32 v118, v120
	v_permlane32_swap_b32_e32 v119, v121
	v_cmp_gt_f32_e32 vcc, 1.0, v215
	s_cbranch_vccz .LA_rs1
	s_and_saveexec_b64 s[60:61], s[4:5]
	ds_write_b32 v234, v215 offset:128
	s_or_b64 exec, exec, s[60:61]
	s_waitcnt lgkmcnt(0)
	v_add_u32_e32 v245, v232, v233
	ds_read_b128 v[220:223], v245 offset:224
	ds_read_b128 v[224:227], v245 offset:192
	ds_read_b128 v[216:219], v245 offset:160
	ds_read_b128 v[212:215], v245 offset:128
	s_waitcnt lgkmcnt(0)
	s_waitcnt lgkmcnt(3)
	v_mul_f32_e32 v44, v44, v220
	v_mul_f32_e32 v45, v45, v221
	v_mul_f32_e32 v46, v46, v222
	v_mul_f32_e32 v47, v47, v223
	s_waitcnt lgkmcnt(2)
	v_mul_f32_e32 v40, v40, v224
	v_mul_f32_e32 v41, v41, v225
	v_mul_f32_e32 v42, v42, v226
	v_mul_f32_e32 v43, v43, v227
	s_waitcnt lgkmcnt(1)
	v_mul_f32_e32 v36, v36, v216
	v_mul_f32_e32 v37, v37, v217
	v_mul_f32_e32 v38, v38, v218
	v_mul_f32_e32 v39, v39, v219
	s_waitcnt lgkmcnt(0)
	v_mul_f32_e32 v32, v32, v212
	v_mul_f32_e32 v33, v33, v213
	v_mul_f32_e32 v34, v34, v214
	v_mul_f32_e32 v35, v35, v215
	v_mul_f32_e32 v60, v60, v220
	v_mul_f32_e32 v61, v61, v221
	v_mul_f32_e32 v62, v62, v222
	v_mul_f32_e32 v63, v63, v223
	v_mul_f32_e32 v56, v56, v224
	v_mul_f32_e32 v57, v57, v225
	v_mul_f32_e32 v58, v58, v226
	v_mul_f32_e32 v59, v59, v227
	v_mul_f32_e32 v52, v52, v216
	v_mul_f32_e32 v53, v53, v217
	v_mul_f32_e32 v54, v54, v218
	v_mul_f32_e32 v55, v55, v219
	v_mul_f32_e32 v48, v48, v212
	v_mul_f32_e32 v49, v49, v213
	v_mul_f32_e32 v50, v50, v214
	v_mul_f32_e32 v51, v51, v215
; #define SBAR() __builtin_amdgcn_sched_barrier(0)
; template <int D0> __device__ __forceinline__ void pv_one(f32x16& od, int vb, bf16x8 pa0, bf16x8 pa1, bf16x8 pa2, bf16x8 pa3) {
;     const s16x4 l0 = tr_read<v_rd_off(D0, 0, 0)>(vb), h0 = tr_read<v_rd_off(D0, 0, 1)>(vb), l1 = tr_read<v_rd_off(D0, 1, 0)>(vb), h1 = tr_read<v_rd_off(D0, 1, 1)>(vb);
;     const s16x4 l2 = tr_read<v_rd_off(D0, 2, 0)>(vb), h2 = tr_read<v_rd_off(D0, 2, 1)>(vb), l3 = tr_read<v_rd_off(D0, 3, 0)>(vb), h3 = tr_read<v_rd_off(D0, 3, 1)>(vb);
;     asm volatile("s_waitcnt lgkmcnt(0)" ::: "memory"); SBAR();
;     ...
;     od = __builtin_amdgcn_mfma_f32_32x32x16_bf16(pa0, PK(l0, h0), od, 0, 0, 0);
;     od = __builtin_amdgcn_mfma_f32_32x32x16_bf16(pa1, PK(l1, h1), od, 0, 0, 0);
;     od = __builtin_amdgcn_mfma_f32_32x32x16_bf16(pa2, PK(l2, h2), od, 0, 0, 0);
;     od = __builtin_amdgcn_mfma_f32_32x32x16_bf16(pa3, PK(l3, h3), od, 0, 0, 0);
.LA_rs1:
	ds_read_b64_tr_b16 v[106:107], v202 offset:512
	ds_read_b64_tr_b16 v[108:109], v202 offset:2560
	ds_read_b64_tr_b16 v[110:111], v202 offset:4608
	ds_read_b64_tr_b16 v[112:113], v202 offset:6656
	ds_read_b64_tr_b16 v[122:123], v202 offset:8704
	ds_read_b64_tr_b16 v[124:125], v202 offset:10752
	ds_read_b64_tr_b16 v[126:127], v202 offset:12800
	ds_read_b64_tr_b16 v[128:129], v202 offset:14848
	s_waitcnt lgkmcnt(8)
	v_mfma_f32_32x32x16_bf16 v[0:15], v[66:69], v[74:77], v[0:15]
	v_mfma_f32_32x32x16_bf16 v[32:47], v[98:101], v[74:77], v[32:47]
	v_mfma_f32_32x32x16_bf16 v[0:15], v[70:73], v[78:81], v[0:15]
	v_mfma_f32_32x32x16_bf16 v[32:47], v[102:105], v[78:81], v[32:47]
	v_mfma_f32_32x32x16_bf16 v[0:15], v[82:85], v[90:93], v[0:15]
	v_mfma_f32_32x32x16_bf16 v[32:47], v[114:117], v[90:93], v[32:47]
	v_mfma_f32_32x32x16_bf16 v[0:15], v[86:89], v[94:97], v[0:15]
	v_mfma_f32_32x32x16_bf16 v[32:47], v[118:121], v[94:97], v[32:47]
	s_waitcnt lgkmcnt(6)
	v_mfma_f32_32x32x16_bf16 v[16:31], v[66:69], v[106:109], v[16:31]
	v_mfma_f32_32x32x16_bf16 v[48:63], v[98:101], v[106:109], v[48:63]
	s_waitcnt lgkmcnt(4)
	v_mfma_f32_32x32x16_bf16 v[16:31], v[70:73], v[110:113], v[16:31]
	v_mfma_f32_32x32x16_bf16 v[48:63], v[102:105], v[110:113], v[48:63]
	s_waitcnt lgkmcnt(2)
	v_mfma_f32_32x32x16_bf16 v[16:31], v[82:85], v[122:125], v[16:31]
	v_mfma_f32_32x32x16_bf16 v[48:63], v[114:117], v[122:125], v[48:63]
	s_waitcnt lgkmcnt(0)
	v_mfma_f32_32x32x16_bf16 v[16:31], v[86:89], v[126:129], v[16:31]
	v_mfma_f32_32x32x16_bf16 v[48:63], v[118:121], v[126:129], v[48:63]
	s_waitcnt lgkmcnt(0)
	s_cmp_eq_u64 s[2:3], 0
	s_cbranch_scc1 .LA_g0b
	s_barrier
